# v65 + nt on the prologue's read-once f32 weight and x loads
# baseline (speedup 1.0000x reference)
.LBB0_78:
	s_waitcnt vmcnt(5)
	v_cmp_lt_i32_e32 vcc, -1, v2
	v_or_b32_e32 v4, s24, v84
	s_ashr_i32 s25, s24, 31
	v_cndmask_b32_e32 v86, 0, v2, vcc
	v_or_b32_e32 v2, s24, v90
	s_waitcnt vmcnt(4)
	v_mul_lo_u32 v6, s41, v4
	v_mad_u64_u32 v[4:5], s[48:49], s40, v4, 0
	s_mul_i32 s35, s40, s25
	v_mul_lo_u32 v10, s41, v2
	v_mad_u64_u32 v[8:9], s[48:49], s40, v2, 0
	v_add3_u32 v5, v5, s35, v6
	v_add3_u32 v9, v9, s35, v10
	v_lshl_add_u64 v[4:5], v[4:5], 2, s[4:5]
	v_lshlrev_b64 v[6:7], 2, v[86:87]
	v_lshl_add_u64 v[8:9], v[8:9], 2, s[4:5]
	v_lshl_add_u64 v[4:5], v[4:5], 0, v[6:7]
	v_lshl_add_u64 v[8:9], v[8:9], 0, v[6:7]
	v_or_b32_e32 v2, s24, v91
	global_load_dwordx4 v[54:57], v[4:5], off nt
	global_load_dwordx4 v[50:53], v[8:9], off nt
	v_mul_lo_u32 v8, s41, v2
	v_mad_u64_u32 v[4:5], s[48:49], s40, v2, 0
	v_or_b32_e32 v2, s24, v92
	v_add3_u32 v5, v5, s35, v8
	v_mul_lo_u32 v10, s41, v2
	v_mad_u64_u32 v[8:9], s[48:49], s40, v2, 0
	v_add3_u32 v9, v9, s35, v10
	v_lshl_add_u64 v[4:5], v[4:5], 2, s[4:5]
	v_lshl_add_u64 v[8:9], v[8:9], 2, s[4:5]
	v_lshl_add_u64 v[4:5], v[4:5], 0, v[6:7]
	v_lshl_add_u64 v[8:9], v[8:9], 0, v[6:7]
	v_or_b32_e32 v2, s24, v93
	global_load_dwordx4 v[62:65], v[4:5], off nt
	global_load_dwordx4 v[58:61], v[8:9], off nt
	v_mul_lo_u32 v8, s41, v2
	v_mad_u64_u32 v[4:5], s[48:49], s40, v2, 0
	v_or_b32_e32 v2, s24, v94
	v_add3_u32 v5, v5, s35, v8
	v_mul_lo_u32 v10, s41, v2
	v_mad_u64_u32 v[8:9], s[48:49], s40, v2, 0
	v_add3_u32 v9, v9, s35, v10
	v_lshl_add_u64 v[4:5], v[4:5], 2, s[4:5]
	v_lshl_add_u64 v[8:9], v[8:9], 2, s[4:5]
	v_lshl_add_u64 v[4:5], v[4:5], 0, v[6:7]
	v_lshl_add_u64 v[8:9], v[8:9], 0, v[6:7]
	v_or_b32_e32 v2, s24, v95
	global_load_dwordx4 v[70:73], v[4:5], off nt
	global_load_dwordx4 v[66:69], v[8:9], off nt
	v_mul_lo_u32 v8, s41, v2
	v_mad_u64_u32 v[4:5], s[48:49], s40, v2, 0
	v_or_b32_e32 v2, s24, v96
	v_add3_u32 v5, v5, s35, v8
	v_mul_lo_u32 v10, s41, v2
	v_mad_u64_u32 v[8:9], s[40:41], s40, v2, 0
	v_lshl_add_u64 v[4:5], v[4:5], 2, s[4:5]
	v_add3_u32 v9, v9, s35, v10
	v_lshl_add_u64 v[4:5], v[4:5], 0, v[6:7]
	v_lshl_add_u64 v[8:9], v[8:9], 2, s[4:5]
	v_lshl_add_u64 v[6:7], v[8:9], 0, v[6:7]
	global_load_dwordx4 v[78:81], v[4:5], off nt
	global_load_dwordx4 v[74:77], v[6:7], off nt
	v_mov_b32_e32 v2, 1.0
	s_cmp_eq_u64 s[36:37], 0
	v_mov_b32_e32 v10, 1.0
	v_mov_b32_e32 v11, 1.0
	v_mov_b32_e32 v12, 1.0
	v_mov_b32_e32 v13, 1.0
	v_mov_b32_e32 v14, 1.0
	v_mov_b32_e32 v15, 1.0
	v_mov_b32_e32 v16, 1.0
	v_mov_b32_e32 v17, 1.0
	s_cbranch_scc1 .LBB0_80
	s_lshl_b64 s[4:5], s[24:25], 2
	s_add_u32 s4, s36, s4
	s_addc_u32 s5, s37, s5
	global_load_dwordx4 v[10:13], v100, s[4:5] offset:16 nt
	global_load_dwordx4 v[14:17], v100, s[4:5] nt
.LBB0_80:
	v_or_b32_e32 v4, s34, v84
	v_mul_lo_u32 v6, s47, v4
	v_mad_u64_u32 v[4:5], s[4:5], s46, v4, 0
	v_cmp_lt_i32_e64 s[4:5], -1, v3
	s_ashr_i32 s35, s34, 31
	s_mul_i32 s40, s46, s35
	v_cndmask_b32_e64 v86, 0, v3, s[4:5]
	v_or_b32_e32 v3, s34, v90
	v_mul_lo_u32 v18, s47, v3
	v_mad_u64_u32 v[8:9], s[36:37], s46, v3, 0
	v_add3_u32 v5, v5, s40, v6
	v_add3_u32 v9, v9, s40, v18
	v_lshl_add_u64 v[4:5], v[4:5], 2, s[42:43]
	v_lshlrev_b64 v[6:7], 2, v[86:87]
	v_lshl_add_u64 v[8:9], v[8:9], 2, s[42:43]
	v_lshl_add_u64 v[4:5], v[4:5], 0, v[6:7]
	v_lshl_add_u64 v[8:9], v[8:9], 0, v[6:7]
	v_or_b32_e32 v3, s34, v91
	global_load_dwordx4 v[22:25], v[4:5], off nt
	global_load_dwordx4 v[18:21], v[8:9], off nt
	v_mul_lo_u32 v8, s47, v3
	v_mad_u64_u32 v[4:5], s[36:37], s46, v3, 0
	v_or_b32_e32 v3, s34, v92
	v_add3_u32 v5, v5, s40, v8
	v_mul_lo_u32 v26, s47, v3
	v_mad_u64_u32 v[8:9], s[36:37], s46, v3, 0
	v_add3_u32 v9, v9, s40, v26
	v_lshl_add_u64 v[4:5], v[4:5], 2, s[42:43]
	v_lshl_add_u64 v[8:9], v[8:9], 2, s[42:43]
	v_lshl_add_u64 v[4:5], v[4:5], 0, v[6:7]
	v_lshl_add_u64 v[8:9], v[8:9], 0, v[6:7]
	v_or_b32_e32 v3, s34, v93
	global_load_dwordx4 v[30:33], v[4:5], off nt
	global_load_dwordx4 v[26:29], v[8:9], off nt
	v_mul_lo_u32 v8, s47, v3
	v_mad_u64_u32 v[4:5], s[36:37], s46, v3, 0
	v_or_b32_e32 v3, s34, v94
	v_add3_u32 v5, v5, s40, v8
	v_mul_lo_u32 v34, s47, v3
	v_mad_u64_u32 v[8:9], s[36:37], s46, v3, 0
	v_add3_u32 v9, v9, s40, v34
	v_lshl_add_u64 v[4:5], v[4:5], 2, s[42:43]
	v_lshl_add_u64 v[8:9], v[8:9], 2, s[42:43]
	v_lshl_add_u64 v[4:5], v[4:5], 0, v[6:7]
	v_lshl_add_u64 v[8:9], v[8:9], 0, v[6:7]
	v_or_b32_e32 v3, s34, v95
	global_load_dwordx4 v[38:41], v[4:5], off nt
	global_load_dwordx4 v[34:37], v[8:9], off nt
	v_mul_lo_u32 v8, s47, v3
	v_mad_u64_u32 v[4:5], s[36:37], s46, v3, 0
	v_or_b32_e32 v3, s34, v96
	v_add3_u32 v5, v5, s40, v8
	v_mul_lo_u32 v42, s47, v3
	v_mad_u64_u32 v[8:9], s[36:37], s46, v3, 0
	v_lshl_add_u64 v[4:5], v[4:5], 2, s[42:43]
	v_add3_u32 v9, v9, s40, v42
	v_lshl_add_u64 v[4:5], v[4:5], 0, v[6:7]
	v_lshl_add_u64 v[8:9], v[8:9], 2, s[42:43]
	v_lshl_add_u64 v[6:7], v[8:9], 0, v[6:7]
	global_load_dwordx4 v[46:49], v[4:5], off nt
	global_load_dwordx4 v[42:45], v[6:7], off nt
	s_cmp_eq_u64 s[44:45], 0
	v_mov_b32_e32 v3, 1.0
	v_mov_b32_e32 v4, 1.0
	v_mov_b32_e32 v5, 1.0
	v_mov_b32_e32 v6, 1.0
	v_mov_b32_e32 v7, 1.0
	v_mov_b32_e32 v8, 1.0
	v_mov_b32_e32 v9, 1.0
	s_cbranch_scc1 .LBB0_82
	s_lshl_b64 s[36:37], s[34:35], 2
	s_add_u32 s36, s44, s36
	s_addc_u32 s37, s45, s37
	global_load_dwordx4 v[2:5], v100, s[36:37] offset:16 nt
	global_load_dwordx4 v[6:9], v100, s[36:37] nt

.LBB0_95:
	s_waitcnt lgkmcnt(0)
	global_load_dwordx4 v[14:17], v[4:5], off offset:-4096 nt
	global_load_dwordx4 v[18:21], v[4:5], off offset:-3072 nt
	global_load_dwordx4 v[22:25], v[4:5], off offset:-2048 nt
	global_load_dwordx4 v[26:29], v[4:5], off offset:-1024 nt
	global_load_dwordx4 v[30:33], v[4:5], off nt
	global_load_dwordx4 v[34:37], v[4:5], off offset:1024 nt
	global_load_dwordx4 v[38:41], v[4:5], off offset:2048 nt
	global_load_dwordx4 v[42:45], v[4:5], off offset:3072 nt
	s_waitcnt vmcnt(7)
	v_cvt_pk_bf16_f32 v14, v14, v15
	v_cvt_pk_bf16_f32 v15, v16, v17
	v_and_b32_e32 v16, 0xffff0000, v14
	v_lshlrev_b32_e32 v1, 16, v14
	v_and_b32_e32 v46, 0xffff0000, v15
	v_mul_f32_e32 v16, v16, v16
	v_lshlrev_b32_e32 v17, 16, v15
	v_fmac_f32_e32 v16, v1, v1
	v_mul_f32_e32 v1, v46, v46
	v_fmac_f32_e32 v1, v17, v17
	v_add_f32_e32 v1, v16, v1
	s_waitcnt vmcnt(6)
	v_cvt_pk_bf16_f32 v16, v18, v19
	v_cvt_pk_bf16_f32 v17, v20, v21
	v_and_b32_e32 v19, 0xffff0000, v16
	v_lshlrev_b32_e32 v18, 16, v16
	v_and_b32_e32 v21, 0xffff0000, v17
	v_mul_f32_e32 v19, v19, v19
	v_lshlrev_b32_e32 v20, 16, v17
	v_fmac_f32_e32 v19, v18, v18
	v_mul_f32_e32 v18, v21, v21
	v_fmac_f32_e32 v18, v20, v20
	v_add_f32_e32 v18, v19, v18
	v_add_f32_e32 v1, v1, v18
	s_waitcnt vmcnt(5)
	v_cvt_pk_bf16_f32 v18, v22, v23
	v_cvt_pk_bf16_f32 v19, v24, v25
	v_and_b32_e32 v21, 0xffff0000, v18
	v_lshlrev_b32_e32 v20, 16, v18
	v_and_b32_e32 v23, 0xffff0000, v19
	v_mul_f32_e32 v21, v21, v21
	v_lshlrev_b32_e32 v22, 16, v19
	v_fmac_f32_e32 v21, v20, v20
	v_mul_f32_e32 v20, v23, v23
	v_fmac_f32_e32 v20, v22, v22
	v_add_f32_e32 v20, v21, v20
	v_add_f32_e32 v1, v1, v20
	s_waitcnt vmcnt(4)
	v_cvt_pk_bf16_f32 v20, v26, v27
	v_cvt_pk_bf16_f32 v21, v28, v29
	v_and_b32_e32 v23, 0xffff0000, v20
	v_lshlrev_b32_e32 v22, 16, v20
	v_and_b32_e32 v25, 0xffff0000, v21
	v_mul_f32_e32 v23, v23, v23
	v_lshlrev_b32_e32 v24, 16, v21
	v_fmac_f32_e32 v23, v22, v22
	v_mul_f32_e32 v22, v25, v25
	v_fmac_f32_e32 v22, v24, v24
	v_add_f32_e32 v22, v23, v22
	v_add_f32_e32 v1, v1, v22
	s_waitcnt vmcnt(3)
	v_cvt_pk_bf16_f32 v22, v30, v31
	v_cvt_pk_bf16_f32 v23, v32, v33
	v_and_b32_e32 v25, 0xffff0000, v22
	v_lshlrev_b32_e32 v24, 16, v22
	v_and_b32_e32 v27, 0xffff0000, v23
	v_mul_f32_e32 v25, v25, v25
	v_lshlrev_b32_e32 v26, 16, v23
	v_fmac_f32_e32 v25, v24, v24
	v_mul_f32_e32 v24, v27, v27
	v_fmac_f32_e32 v24, v26, v26
	v_add_f32_e32 v24, v25, v24
	v_add_f32_e32 v1, v1, v24
	s_waitcnt vmcnt(2)
	v_cvt_pk_bf16_f32 v24, v34, v35
	v_cvt_pk_bf16_f32 v25, v36, v37
	v_and_b32_e32 v27, 0xffff0000, v24
	v_lshlrev_b32_e32 v26, 16, v24
	v_and_b32_e32 v29, 0xffff0000, v25
	v_mul_f32_e32 v27, v27, v27
	v_lshlrev_b32_e32 v28, 16, v25
	v_fmac_f32_e32 v27, v26, v26
	v_mul_f32_e32 v26, v29, v29
	v_fmac_f32_e32 v26, v28, v28
	v_add_f32_e32 v26, v27, v26
	v_add_f32_e32 v1, v1, v26
	s_waitcnt vmcnt(1)
	v_cvt_pk_bf16_f32 v26, v38, v39
	v_cvt_pk_bf16_f32 v27, v40, v41
	v_and_b32_e32 v29, 0xffff0000, v26
	v_lshlrev_b32_e32 v28, 16, v26
	v_and_b32_e32 v31, 0xffff0000, v27
	v_mul_f32_e32 v29, v29, v29
	v_lshlrev_b32_e32 v30, 16, v27
	v_fmac_f32_e32 v29, v28, v28
	v_mul_f32_e32 v28, v31, v31
	v_fmac_f32_e32 v28, v30, v30
	v_add_f32_e32 v28, v29, v28
	v_add_f32_e32 v1, v1, v28
	s_waitcnt vmcnt(0)
	v_cvt_pk_bf16_f32 v28, v42, v43
	v_cvt_pk_bf16_f32 v29, v44, v45
	v_and_b32_e32 v31, 0xffff0000, v28
	v_lshlrev_b32_e32 v30, 16, v28
	v_and_b32_e32 v33, 0xffff0000, v29
	v_mul_f32_e32 v31, v31, v31
	v_lshlrev_b32_e32 v32, 16, v29
	v_fmac_f32_e32 v31, v30, v30
	v_mul_f32_e32 v30, v33, v33
	v_fmac_f32_e32 v30, v32, v32
	v_add_f32_e32 v30, v31, v30
	v_add_f32_e32 v1, v1, v30
	ds_bpermute_b32 v30, v8, v1
	global_store_dwordx2 v[6:7], v[14:15], off offset:-2048
	global_store_dwordx2 v[6:7], v[16:17], off offset:-1536
	global_store_dwordx2 v[6:7], v[18:19], off offset:-1024
	global_store_dwordx2 v[6:7], v[20:21], off offset:-512
	global_store_dwordx2 v[6:7], v[22:23], off
	global_store_dwordx2 v[6:7], v[24:25], off offset:512
	global_store_dwordx2 v[6:7], v[26:27], off offset:1024
	global_store_dwordx2 v[6:7], v[28:29], off offset:1536
	s_waitcnt lgkmcnt(0)
	v_add_f32_e32 v1, v1, v30
	ds_bpermute_b32 v30, v9, v1
	s_waitcnt lgkmcnt(0)
	v_add_f32_e32 v1, v1, v30
	ds_bpermute_b32 v30, v10, v1
	s_waitcnt lgkmcnt(0)
	v_add_f32_e32 v1, v1, v30
	ds_bpermute_b32 v30, v11, v1
	s_waitcnt lgkmcnt(0)
	v_add_f32_e32 v1, v1, v30
	ds_bpermute_b32 v30, v12, v1
	s_waitcnt lgkmcnt(0)
	v_add_f32_e32 v1, v1, v30
	ds_bpermute_b32 v14, v13, v1
	s_and_saveexec_b64 s[12:13], vcc
	s_cbranch_execz .LBB0_94
	s_waitcnt lgkmcnt(0)
	v_add_f32_e32 v1, v1, v14
	v_cndmask_b32_e64 v1, 0, v1, s[4:5]
	global_store_dword v[2:3], v1, off
	s_branch .LBB0_94
